# T21 epilogue split across waves 0-3 combined with the emission split (QD half in step-5 idle time, KDT half in the T21 slot)
# baseline (speedup 1.0000x reference)
.LBB0_236:
	v_lshlrev_b32_e32 v88, 3, v95
	s_cmp_lt_u32 s48, 4
	v_or_b32_e32 v89, 16, v88
	s_waitcnt lgkmcnt(0)
	s_barrier
	s_cbranch_scc1 .LBB0_245
	s_cmp_gt_u32 s48, 3
	s_cbranch_scc0 .Lem_skip
	s_add_i32 s6, s48, -4
	v_lshlrev_b32_e32 v4, 11, v95
	v_lshlrev_b32_e32 v8, 4, v95
	s_lshl_b32 s7, s6, 6
	v_lshl_add_u32 v4, v94, 2, v4
	v_add_u32_e32 v8, s7, v8
	s_lshl_b32 s7, s6, 13
	s_add_i32 s7, s7, 0x8000
	v_add_u32_e32 v8, 0x24c00, v8
	v_add_u32_e32 v4, s7, v4
	s_lshl_b32 s7, s6, 10
	s_add_i32 s7, s7, s51
	v_add_u32_e32 v5, 0x80, v4
	v_lshl_add_u32 v9, v93, 4, s7
	ds_read_b128 v[186:189], v8
	ds_read_b128 v[190:193], v8 offset:32
	ds_read2st64_b32 v[194:195], v4 offset1:2
	ds_read2st64_b32 v[196:197], v4 offset0:4 offset1:6
	ds_read2st64_b32 v[198:199], v4 offset0:16 offset1:18
	ds_read2st64_b32 v[200:201], v4 offset0:20 offset1:22
	ds_read2st64_b32 v[202:203], v5 offset1:2
	ds_read2st64_b32 v[204:205], v5 offset0:4 offset1:6
	ds_read2st64_b32 v[206:207], v5 offset0:16 offset1:18
	ds_read2st64_b32 v[208:209], v5 offset0:20 offset1:22
	s_waitcnt lgkmcnt(4)
	ds_read2st64_b32 v[210:211], v4 offset0:1 offset1:3
	ds_read2st64_b32 v[212:213], v4 offset0:5 offset1:7
	ds_read2st64_b32 v[214:215], v4 offset0:17 offset1:19
	ds_read2st64_b32 v[216:217], v4 offset0:21 offset1:23
	ds_read2st64_b32 v[106:107], v5 offset0:1 offset1:3
	ds_read2st64_b32 v[108:109], v5 offset0:5 offset1:7
	ds_read2st64_b32 v[110:111], v5 offset0:17 offset1:19
	ds_read2st64_b32 v[112:113], v5 offset0:21 offset1:23
	v_pk_mul_f32 v[194:195], v[194:195], v[186:187]
	v_pk_mul_f32 v[196:197], v[196:197], v[188:189]
	v_pk_mul_f32 v[198:199], v[198:199], v[190:191]
	v_pk_mul_f32 v[200:201], v[200:201], v[192:193]
	v_cvt_pk_bf16_f32 v30, v194, v195
	v_cvt_pk_bf16_f32 v31, v196, v197
	v_cvt_pk_bf16_f32 v32, v198, v199
	v_cvt_pk_bf16_f32 v33, v200, v201
	v_add_u32_e32 v6, 0xa000, v9
	buffer_store_dwordx4 v[30:33], v6, s[72:75], 0 offen sc1
	s_waitcnt lgkmcnt(8)
	v_pk_mul_f32 v[202:203], v[202:203], v[186:187]
	v_pk_mul_f32 v[204:205], v[204:205], v[188:189]
	v_pk_mul_f32 v[206:207], v[206:207], v[190:191]
	v_pk_mul_f32 v[208:209], v[208:209], v[192:193]
	v_cvt_pk_bf16_f32 v114, v202, v203
	v_cvt_pk_bf16_f32 v115, v204, v205
	v_cvt_pk_bf16_f32 v116, v206, v207
	v_cvt_pk_bf16_f32 v117, v208, v209
	v_add_u32_e32 v7, 0xb000, v9
	buffer_store_dwordx4 v[114:117], v7, s[72:75], 0 offen sc1
	s_waitcnt lgkmcnt(4)
	v_pk_mul_f32 v[210:211], v[210:211], v[186:187]
	v_pk_mul_f32 v[212:213], v[212:213], v[188:189]
	v_pk_mul_f32 v[214:215], v[214:215], v[190:191]
	v_pk_mul_f32 v[216:217], v[216:217], v[192:193]
	v_cvt_pk_bf16_f32 v118, v210, v211
	v_cvt_pk_bf16_f32 v119, v212, v213
	v_cvt_pk_bf16_f32 v120, v214, v215
	v_cvt_pk_bf16_f32 v121, v216, v217
	v_add_u32_e32 v6, 0xc000, v9
	buffer_store_dwordx4 v[118:121], v6, s[72:75], 0 offen sc1
	s_waitcnt lgkmcnt(0)
	v_pk_mul_f32 v[106:107], v[106:107], v[186:187]
	v_pk_mul_f32 v[108:109], v[108:109], v[188:189]
	v_pk_mul_f32 v[110:111], v[110:111], v[190:191]
	v_pk_mul_f32 v[112:113], v[112:113], v[192:193]
	v_cvt_pk_bf16_f32 v122, v106, v107
	v_cvt_pk_bf16_f32 v123, v108, v109
	v_cvt_pk_bf16_f32 v124, v110, v111
	v_cvt_pk_bf16_f32 v125, v112, v113
	v_add_u32_e32 v7, 0xd000, v9
	buffer_store_dwordx4 v[122:125], v7, s[72:75], 0 offen sc1
